# in_proj K-loop: drop the store-drain vmcnt(0) at unit entry (only stores outstanding there; counted vmcnt(6) protocol covers the DMA tiles)
# speedup vs baseline: 1.0154x; 1.0005x over previous
.LBB0_211:
	s_ashr_i32 s41, s40, 31
	v_cmp_lt_i64_e32 vcc, s[8:9], v[160:161]
	s_lshl_b64 s[8:9], s[40:41], 19
	s_add_u32 s42, s47, s8
	s_addc_u32 s43, s48, s9
	s_and_b64 s[8:9], vcc, exec
	s_cselect_b32 s1, s43, s3
	s_cselect_b32 s33, s42, s2
	s_ashr_i32 s39, s38, 31
	s_lshl_b64 s[8:9], s[38:39], 19
	s_add_u32 s44, s94, s8
	s_addc_u32 s45, s95, s9
	s_and_b64 s[8:9], vcc, exec
	s_cselect_b32 s39, s45, s7
	s_cselect_b32 s41, s44, s6
	s_add_u32 s2, s2, 0x40080
	s_addc_u32 s3, s3, 0
	s_add_u32 s71, s6, 0x100
	s_addc_u32 s72, s7, 0
	s_mov_b32 s73, -2
.Lpeel_p1:
	ds_read_b128 v[130:133], v173
	ds_read_b128 v[134:137], v173 offset:1024
	ds_read_b128 v[138:141], v173 offset:2048
	ds_read_b128 v[142:145], v173 offset:3072
	s_add_u32 s6, s2, 0xfffc0080
	s_addc_u32 s7, s3, -1
	s_cmp_eq_u32 s73, 12
	s_cselect_b32 s9, s1, s7
	s_cselect_b32 s8, s33, s6
	s_cselect_b32 s7, s39, s72
	s_cselect_b32 s6, s41, s71
	s_add_i32 m0, s50, 0xc000
	ds_read_b128 v[180:183], v175
	ds_read_b128 v[184:187], v175 offset:1024
	ds_read_b128 v[190:193], v175 offset:2048
	ds_read_b128 v[194:197], v175 offset:3072
	ds_read_b128 v[198:201], v175 offset:4096
	ds_read_b128 v[202:205], v175 offset:5120
	ds_read_b128 v[206:209], v175 offset:6144
	ds_read_b128 v[210:213], v175 offset:7168
	global_load_lds_dwordx4 v156, s[2:3]
	s_add_i32 m0, s50, 0xe000
	s_nop 0
	global_load_lds_dwordx4 v158, s[2:3]
	s_waitcnt lgkmcnt(8)
	s_barrier
	s_waitcnt lgkmcnt(0)
	s_setprio 1
	s_waitcnt lgkmcnt(0)
	v_mfma_f32_16x16x32_bf16 v[126:129], v[130:133], v[180:183], 0
	v_mfma_f32_16x16x32_bf16 v[122:125], v[138:141], v[180:183], 0
	v_mfma_f32_16x16x32_bf16 v[118:121], v[130:133], v[190:193], 0
	v_mfma_f32_16x16x32_bf16 v[110:113], v[138:141], v[190:193], 0
	v_mfma_f32_16x16x32_bf16 v[102:105], v[130:133], v[198:201], 0
	v_mfma_f32_16x16x32_bf16 v[94:97], v[138:141], v[198:201], 0
	v_mfma_f32_16x16x32_bf16 v[86:89], v[130:133], v[206:209], 0
	v_mfma_f32_16x16x32_bf16 v[78:81], v[138:141], v[206:209], 0
	v_mfma_f32_16x16x32_bf16 v[126:129], v[134:137], v[184:187], v[126:129]
	v_mfma_f32_16x16x32_bf16 v[122:125], v[142:145], v[184:187], v[122:125]
	v_mfma_f32_16x16x32_bf16 v[118:121], v[134:137], v[194:197], v[118:121]
	v_mfma_f32_16x16x32_bf16 v[110:113], v[142:145], v[194:197], v[110:113]
	v_mfma_f32_16x16x32_bf16 v[102:105], v[134:137], v[202:205], v[102:105]
	v_mfma_f32_16x16x32_bf16 v[94:97], v[142:145], v[202:205], v[94:97]
	v_mfma_f32_16x16x32_bf16 v[86:89], v[134:137], v[210:213], v[86:89]
	v_mfma_f32_16x16x32_bf16 v[78:81], v[142:145], v[210:213], v[78:81]
	s_setprio 0
	s_barrier
	s_add_i32 s74, s66, s49
	s_add_u32 s98, s6, 0x80
	s_addc_u32 s99, s7, 0
	s_mov_b32 m0, s74
	ds_read_b128 v[214:217], v177
	ds_read_b128 v[218:221], v177 offset:1024
	ds_read_b128 v[222:225], v177 offset:2048
	ds_read_b128 v[226:229], v177 offset:3072
	global_load_lds_dwordx4 v148, s[6:7]
	s_add_i32 m0, s74, 0x2000
	s_nop 0
	global_load_lds_dwordx4 v152, s[6:7]
	s_barrier
	s_waitcnt lgkmcnt(0)
	s_setprio 1
	s_waitcnt lgkmcnt(0)
	v_mfma_f32_16x16x32_bf16 v[114:117], v[214:217], v[180:183], 0
	v_mfma_f32_16x16x32_bf16 v[106:109], v[222:225], v[180:183], 0
	v_mfma_f32_16x16x32_bf16 v[98:101], v[214:217], v[190:193], 0
	v_mfma_f32_16x16x32_bf16 v[90:93], v[222:225], v[190:193], 0
	v_mfma_f32_16x16x32_bf16 v[82:85], v[214:217], v[198:201], 0
	v_mfma_f32_16x16x32_bf16 v[74:77], v[222:225], v[198:201], 0
	v_mfma_f32_16x16x32_bf16 v[70:73], v[214:217], v[206:209], 0
	v_mfma_f32_16x16x32_bf16 v[66:69], v[222:225], v[206:209], 0
	v_mfma_f32_16x16x32_bf16 v[114:117], v[218:221], v[184:187], v[114:117]
	v_mfma_f32_16x16x32_bf16 v[106:109], v[226:229], v[184:187], v[106:109]
	v_mfma_f32_16x16x32_bf16 v[98:101], v[218:221], v[194:197], v[98:101]
	v_mfma_f32_16x16x32_bf16 v[90:93], v[226:229], v[194:197], v[90:93]
	v_mfma_f32_16x16x32_bf16 v[82:85], v[218:221], v[202:205], v[82:85]
	v_mfma_f32_16x16x32_bf16 v[74:77], v[226:229], v[202:205], v[74:77]
	v_mfma_f32_16x16x32_bf16 v[70:73], v[218:221], v[210:213], v[70:73]
	v_mfma_f32_16x16x32_bf16 v[66:69], v[226:229], v[210:213], v[66:69]
	s_setprio 0
	s_mov_b32 m0, s50
	s_add_u32 s100, s8, 0x80
	s_addc_u32 s101, s9, 0
	s_barrier
	ds_read_b128 v[180:183], v175 offset:16384
	ds_read_b128 v[184:187], v175 offset:17408
	ds_read_b128 v[190:193], v175 offset:18432
	ds_read_b128 v[194:197], v175 offset:19456
	ds_read_b128 v[198:201], v175 offset:20480
	ds_read_b128 v[202:205], v175 offset:21504
	ds_read_b128 v[206:209], v175 offset:22528
	ds_read_b128 v[210:213], v175 offset:23552
	global_load_lds_dwordx4 v146, s[8:9]
	s_mov_b32 m0, s51
	s_nop 0
	global_load_lds_dwordx4 v150, s[8:9]
	s_barrier
	s_waitcnt lgkmcnt(0)
	s_setprio 1
	s_waitcnt lgkmcnt(0)
	v_mfma_f32_16x16x32_bf16 v[62:65], v[130:133], v[180:183], 0
	v_mfma_f32_16x16x32_bf16 v[58:61], v[138:141], v[180:183], 0
	v_mfma_f32_16x16x32_bf16 v[54:57], v[130:133], v[190:193], 0
	v_mfma_f32_16x16x32_bf16 v[46:49], v[138:141], v[190:193], 0
	v_mfma_f32_16x16x32_bf16 v[38:41], v[130:133], v[198:201], 0
	v_mfma_f32_16x16x32_bf16 v[30:33], v[138:141], v[198:201], 0
	v_mfma_f32_16x16x32_bf16 v[22:25], v[130:133], v[206:209], 0
	v_mfma_f32_16x16x32_bf16 v[14:17], v[138:141], v[206:209], 0
	v_mfma_f32_16x16x32_bf16 v[62:65], v[134:137], v[184:187], v[62:65]
	v_mfma_f32_16x16x32_bf16 v[58:61], v[142:145], v[184:187], v[58:61]
	v_mfma_f32_16x16x32_bf16 v[54:57], v[134:137], v[194:197], v[54:57]
	v_mfma_f32_16x16x32_bf16 v[46:49], v[142:145], v[194:197], v[46:49]
	v_mfma_f32_16x16x32_bf16 v[38:41], v[134:137], v[202:205], v[38:41]
	v_mfma_f32_16x16x32_bf16 v[30:33], v[142:145], v[202:205], v[30:33]
	v_mfma_f32_16x16x32_bf16 v[22:25], v[134:137], v[210:213], v[22:25]
	v_mfma_f32_16x16x32_bf16 v[14:17], v[142:145], v[210:213], v[14:17]
	s_setprio 0
	s_barrier
	s_add_u32 s74, s6, 0x40000
	s_addc_u32 s75, s7, 0
	s_add_i32 s76, s67, s49
	s_mov_b32 m0, s76
	s_nop 0
	global_load_lds_dwordx4 v148, s[74:75]
	s_add_i32 m0, s76, 0x2000
	s_nop 0
	global_load_lds_dwordx4 v152, s[74:75]
	s_waitcnt vmcnt(6)
	s_barrier
	s_setprio 1
	v_mfma_f32_16x16x32_bf16 v[50:53], v[214:217], v[180:183], 0
	v_mfma_f32_16x16x32_bf16 v[42:45], v[222:225], v[180:183], 0
	v_mfma_f32_16x16x32_bf16 v[34:37], v[214:217], v[190:193], 0
	v_mfma_f32_16x16x32_bf16 v[26:29], v[222:225], v[190:193], 0
	v_mfma_f32_16x16x32_bf16 v[18:21], v[214:217], v[198:201], 0
	v_mfma_f32_16x16x32_bf16 v[10:13], v[222:225], v[198:201], 0
	v_mfma_f32_16x16x32_bf16 v[6:9], v[214:217], v[206:209], 0
	v_mfma_f32_16x16x32_bf16 v[2:5], v[222:225], v[206:209], 0
	v_mfma_f32_16x16x32_bf16 v[50:53], v[218:221], v[184:187], v[50:53]
	v_mfma_f32_16x16x32_bf16 v[42:45], v[226:229], v[184:187], v[42:45]
	v_mfma_f32_16x16x32_bf16 v[34:37], v[218:221], v[194:197], v[34:37]
	v_mfma_f32_16x16x32_bf16 v[26:29], v[226:229], v[194:197], v[26:29]
	v_mfma_f32_16x16x32_bf16 v[18:21], v[218:221], v[202:205], v[18:21]
	v_mfma_f32_16x16x32_bf16 v[10:13], v[226:229], v[202:205], v[10:13]
	v_mfma_f32_16x16x32_bf16 v[6:9], v[218:221], v[210:213], v[6:9]
	v_mfma_f32_16x16x32_bf16 v[2:5], v[226:229], v[210:213], v[2:5]
	s_setprio 0
	s_add_i32 s74, 0, 0x18000
	v_add_u32_e32 v142, s74, v171
	s_barrier
	ds_read_b128 v[130:133], v142
	ds_read_b128 v[134:137], v142 offset:1024
	ds_read_b128 v[138:141], v142 offset:2048
	ds_read_b128 v[142:145], v142 offset:3072
	s_add_u32 s8, s8, 0x40000
	s_addc_u32 s9, s9, 0
	s_mov_b32 m0, s52
	ds_read_b128 v[180:183], v175 offset:32768
	ds_read_b128 v[184:187], v175 offset:33792
	ds_read_b128 v[190:193], v175 offset:34816
	ds_read_b128 v[194:197], v175 offset:35840
	ds_read_b128 v[198:201], v175 offset:36864
	ds_read_b128 v[202:205], v175 offset:37888
	ds_read_b128 v[206:209], v175 offset:38912
	ds_read_b128 v[210:213], v175 offset:39936
	global_load_lds_dwordx4 v146, s[8:9]
	s_mov_b32 m0, s53
	s_nop 0
	global_load_lds_dwordx4 v150, s[8:9]
	s_waitcnt lgkmcnt(8)
	s_barrier
	s_waitcnt lgkmcnt(0)
	s_setprio 1
	s_waitcnt lgkmcnt(0)
	v_mfma_f32_16x16x32_bf16 v[126:129], v[130:133], v[180:183], v[126:129]
	v_mfma_f32_16x16x32_bf16 v[122:125], v[138:141], v[180:183], v[122:125]
	v_mfma_f32_16x16x32_bf16 v[118:121], v[130:133], v[190:193], v[118:121]
	v_mfma_f32_16x16x32_bf16 v[110:113], v[138:141], v[190:193], v[110:113]
	v_mfma_f32_16x16x32_bf16 v[102:105], v[130:133], v[198:201], v[102:105]
	v_mfma_f32_16x16x32_bf16 v[94:97], v[138:141], v[198:201], v[94:97]
	v_mfma_f32_16x16x32_bf16 v[86:89], v[130:133], v[206:209], v[86:89]
	v_mfma_f32_16x16x32_bf16 v[78:81], v[138:141], v[206:209], v[78:81]
	v_mfma_f32_16x16x32_bf16 v[126:129], v[134:137], v[184:187], v[126:129]
	v_mfma_f32_16x16x32_bf16 v[122:125], v[142:145], v[184:187], v[122:125]
	v_mfma_f32_16x16x32_bf16 v[118:121], v[134:137], v[194:197], v[118:121]
	v_mfma_f32_16x16x32_bf16 v[110:113], v[142:145], v[194:197], v[110:113]
	v_mfma_f32_16x16x32_bf16 v[102:105], v[134:137], v[202:205], v[102:105]
	v_mfma_f32_16x16x32_bf16 v[94:97], v[142:145], v[202:205], v[94:97]
	v_mfma_f32_16x16x32_bf16 v[86:89], v[134:137], v[210:213], v[86:89]
	v_mfma_f32_16x16x32_bf16 v[78:81], v[142:145], v[210:213], v[78:81]
	s_setprio 0
	s_barrier
	s_add_i32 s8, 0, 0x1c000
	s_add_i32 s9, s74, s49
	v_add_u32_e32 v154, s8, v171
	s_mov_b32 m0, s9
	ds_read_b128 v[214:217], v154
	ds_read_b128 v[218:221], v154 offset:1024
	ds_read_b128 v[222:225], v154 offset:2048
	ds_read_b128 v[226:229], v154 offset:3072
	global_load_lds_dwordx4 v148, s[98:99]
	s_add_i32 m0, s9, 0x2000
	s_nop 0
	global_load_lds_dwordx4 v152, s[98:99]
	s_barrier
	s_waitcnt lgkmcnt(0)
	s_setprio 1
	s_waitcnt lgkmcnt(0)
	v_mfma_f32_16x16x32_bf16 v[114:117], v[214:217], v[180:183], v[114:117]
	v_mfma_f32_16x16x32_bf16 v[106:109], v[222:225], v[180:183], v[106:109]
	v_mfma_f32_16x16x32_bf16 v[98:101], v[214:217], v[190:193], v[98:101]
	v_mfma_f32_16x16x32_bf16 v[90:93], v[222:225], v[190:193], v[90:93]
	v_mfma_f32_16x16x32_bf16 v[82:85], v[214:217], v[198:201], v[82:85]
	v_mfma_f32_16x16x32_bf16 v[74:77], v[222:225], v[198:201], v[74:77]
	v_mfma_f32_16x16x32_bf16 v[70:73], v[214:217], v[206:209], v[70:73]
	v_mfma_f32_16x16x32_bf16 v[66:69], v[222:225], v[206:209], v[66:69]
	v_mfma_f32_16x16x32_bf16 v[114:117], v[218:221], v[184:187], v[114:117]
	v_mfma_f32_16x16x32_bf16 v[106:109], v[226:229], v[184:187], v[106:109]
	v_mfma_f32_16x16x32_bf16 v[98:101], v[218:221], v[194:197], v[98:101]
	v_mfma_f32_16x16x32_bf16 v[90:93], v[226:229], v[194:197], v[90:93]
	v_mfma_f32_16x16x32_bf16 v[82:85], v[218:221], v[202:205], v[82:85]
	v_mfma_f32_16x16x32_bf16 v[74:77], v[226:229], v[202:205], v[74:77]
	v_mfma_f32_16x16x32_bf16 v[70:73], v[218:221], v[210:213], v[70:73]
	v_mfma_f32_16x16x32_bf16 v[66:69], v[226:229], v[210:213], v[66:69]
	s_setprio 0
	s_mov_b32 m0, s56
	s_barrier
	ds_read_b128 v[180:183], v175 offset:49152
	ds_read_b128 v[184:187], v175 offset:50176
	ds_read_b128 v[190:193], v175 offset:51200
	ds_read_b128 v[194:197], v175 offset:52224
	ds_read_b128 v[198:201], v175 offset:53248
	ds_read_b128 v[202:205], v175 offset:54272
	ds_read_b128 v[206:209], v175 offset:55296
	ds_read_b128 v[210:213], v175 offset:56320
	global_load_lds_dwordx4 v146, s[100:101]
	s_mov_b32 m0, s57
	s_nop 0
	global_load_lds_dwordx4 v150, s[100:101]
	s_barrier
	s_waitcnt lgkmcnt(0)
	s_setprio 1
	s_waitcnt lgkmcnt(0)
	v_mfma_f32_16x16x32_bf16 v[62:65], v[130:133], v[180:183], v[62:65]
	v_mfma_f32_16x16x32_bf16 v[58:61], v[138:141], v[180:183], v[58:61]
	v_mfma_f32_16x16x32_bf16 v[54:57], v[130:133], v[190:193], v[54:57]
	v_mfma_f32_16x16x32_bf16 v[46:49], v[138:141], v[190:193], v[46:49]
	v_mfma_f32_16x16x32_bf16 v[38:41], v[130:133], v[198:201], v[38:41]
	v_mfma_f32_16x16x32_bf16 v[30:33], v[138:141], v[198:201], v[30:33]
	v_mfma_f32_16x16x32_bf16 v[22:25], v[130:133], v[206:209], v[22:25]
	v_mfma_f32_16x16x32_bf16 v[14:17], v[138:141], v[206:209], v[14:17]
	v_mfma_f32_16x16x32_bf16 v[62:65], v[134:137], v[184:187], v[62:65]
	v_mfma_f32_16x16x32_bf16 v[58:61], v[142:145], v[184:187], v[58:61]
	v_mfma_f32_16x16x32_bf16 v[54:57], v[134:137], v[194:197], v[54:57]
	v_mfma_f32_16x16x32_bf16 v[46:49], v[142:145], v[194:197], v[46:49]
	v_mfma_f32_16x16x32_bf16 v[38:41], v[134:137], v[202:205], v[38:41]
	v_mfma_f32_16x16x32_bf16 v[30:33], v[142:145], v[202:205], v[30:33]
	v_mfma_f32_16x16x32_bf16 v[22:25], v[134:137], v[210:213], v[22:25]
	v_mfma_f32_16x16x32_bf16 v[14:17], v[142:145], v[210:213], v[14:17]
	s_setprio 0
	s_barrier
	s_add_u32 s6, s6, 0x40080
	s_addc_u32 s7, s7, 0
	s_add_i32 s8, s8, s49
	s_mov_b32 m0, s8
	s_nop 0
	global_load_lds_dwordx4 v148, s[6:7]
	s_add_i32 m0, s8, 0x2000
	s_nop 0
	global_load_lds_dwordx4 v152, s[6:7]
	s_waitcnt vmcnt(6)
	s_barrier
	s_setprio 1
	v_mfma_f32_16x16x32_bf16 v[50:53], v[214:217], v[180:183], v[50:53]
	v_mfma_f32_16x16x32_bf16 v[42:45], v[222:225], v[180:183], v[42:45]
	v_mfma_f32_16x16x32_bf16 v[34:37], v[214:217], v[190:193], v[34:37]
	v_mfma_f32_16x16x32_bf16 v[26:29], v[222:225], v[190:193], v[26:29]
	v_mfma_f32_16x16x32_bf16 v[18:21], v[214:217], v[198:201], v[18:21]
	v_mfma_f32_16x16x32_bf16 v[10:13], v[222:225], v[198:201], v[10:13]
	v_mfma_f32_16x16x32_bf16 v[6:9], v[214:217], v[206:209], v[6:9]
	v_mfma_f32_16x16x32_bf16 v[2:5], v[222:225], v[206:209], v[2:5]
	v_mfma_f32_16x16x32_bf16 v[50:53], v[218:221], v[184:187], v[50:53]
	v_mfma_f32_16x16x32_bf16 v[42:45], v[226:229], v[184:187], v[42:45]
	v_mfma_f32_16x16x32_bf16 v[34:37], v[218:221], v[194:197], v[34:37]
	v_mfma_f32_16x16x32_bf16 v[26:29], v[226:229], v[194:197], v[26:29]
	v_mfma_f32_16x16x32_bf16 v[18:21], v[218:221], v[202:205], v[18:21]
	v_mfma_f32_16x16x32_bf16 v[10:13], v[226:229], v[202:205], v[10:13]
	v_mfma_f32_16x16x32_bf16 v[6:9], v[218:221], v[210:213], v[6:9]
	v_mfma_f32_16x16x32_bf16 v[2:5], v[226:229], v[210:213], v[2:5]
	s_setprio 0
	s_add_i32 s73, s73, 2
	s_add_u32 s2, s2, 0x100
	s_addc_u32 s3, s3, 0
	s_add_u32 s71, s71, 0x100
	s_addc_u32 s72, s72, 0
	s_cmp_gt_u32 s73, 13
	s_barrier
	s_cbranch_scc1 .Lpeel_p1_exit
